# speedup vs baseline: 1.0011x; 1.0011x over previous
; __device__ __forceinline__ int opaque_tid() { int t = threadIdx.x; asm volatile("" : "+v"(t)); return t; }
; template <int BN, bool SWAP> ...
;     ...
;   const int tid = opaque_tid(), lane = tid & 63, wave = tid >> 6;
;   const int wr = wave >> 1, wc = wave & 1, c15 = lane & 15, g = lane >> 4;
;   bfu* As = sm;
;   bfu* Bs = sm + 2 * 128 * 72;
;   const int lrow = tid >> 3, lch = (tid & 7) * 8;
;   const bfu* Ap = A + (size_t)lrow * lda + lch;
;   const bfu* Bp = B + (size_t)lrow * ldb + lch;
;   int brow = lrow;
;   if (SWAP) {
;     if (NJ == 4) brow = ((lrow & 12) << 2) | ((lrow >> 2) & 4) | (lrow & 3);
;     else brow = ((lrow & 4) << 2) | ((lrow >> 1) & 12) | (lrow & 3);
;   }
;   const int nk = K >> 6;
;   const bool chain = (An != nullptr);
;   const bfu* Apn = chain ? (An + (size_t)lrow * ldan + lch) : Ap;
;   const bfu* Bpn = chain ? (Bn + (size_t)lrow * ldbn + lch) : Bp;
;   auto gl = [&](bf16x8 (&ra)[4], bf16x8 (&rb)[NJ], int kt) {
;     const bool nx = (kt >= nk);
;     const bfu* pa = nx ? (chain ? Apn + (kt - nk) * 64 : Ap + (nk - 1) * 64) : Ap + kt * 64;
;     const bfu* pb = nx ? (chain ? Bpn + (kt - nk) * 64 : Bp + (nk - 1) * 64) : Bp + kt * 64;
;     const size_t sa = (nx && chain) ? (size_t)ldan : (size_t)lda, sb = (nx && chain) ? (size_t)ldbn : (size_t)ldb;
; #pragma unroll
;     for (int q = 0; q < 4; ++q) ra[q] = gld16(pa + (size_t)(32 * q) * sa);
; #pragma unroll
;     for (int q = 0; q < NJ; ++q) rb[q] = gld16(pb + (size_t)(32 * q) * sb);
;   };
;   auto wt = [&](bf16x8 (&ra)[4], bf16x8 (&rb)[NJ]) {
;     if (NJ == 4) asm volatile("s_waitcnt vmcnt(8)" : "+v"(ra[0]), "+v"(ra[1]), "+v"(ra[2]), "+v"(ra[3]), "+v"(rb[0]), "+v"(rb[1]), "+v"(rb[NJ - 2]), "+v"(rb[NJ - 1]) : : "memory");
; template <int G>
; __device__ __forceinline__ void p5(const Params& P, const Ptrs<G>& w, int pass, int layer, bfu* sm, const XcdInfo& xi) {
;     ...
;   for (int tile = tstart; tile < tend; tile += tstep) {
;     int nt, mt;
;     if (xi.ok) xcd_tile(tile, xi.x, MT / 8, 8, mt, nt); else { nt = tile / MT; mt = tile % MT; }
;     const int n0 = nt * 128, m0 = mt * 128;
;     f32x4 C[4][4];
; #pragma unroll
;     for (int i = 0; i < 4; ++i)
; #pragma unroll
;       for (int j = 0; j < 4; ++j) C[i][j] = (f32x4){0.f, 0.f, 0.f, 0.f};
;     gemm_loop<128, true>(w.merged() + (size_t)m0 * 1024, 1024, Wl + L::W_IN + L::W_B + (size_t)n0 * 1024, 1024, 1024, C, sm);
.LBB0_484:
	s_lshl_b32 s12, s14, 7
	s_lshl_b32 s14, s2, 7
	s_ashr_i32 s15, s14, 31
	s_lshl_b64 s[20:21], s[14:15], 11
	s_add_u32 s20, s70, s20
	s_addc_u32 s21, s71, s21
	s_ashr_i32 s13, s12, 31
	v_mov_b32_e32 v38, v174
	s_lshl_b64 s[22:23], s[12:13], 11
	s_add_u32 s22, s16, s22
	v_ashrrev_i32_e32 v32, 3, v38
	v_ashrrev_i32_e32 v33, 31, v32
	s_addc_u32 s23, s17, s23
	v_lshlrev_b64 v[0:1], 11, v[32:33]
	v_lshlrev_b32_e32 v4, 4, v38
	v_lshl_add_u64 v[2:3], s[20:21], 0, v[0:1]
	v_and_b32_e32 v152, 0x70, v4
	v_lshl_add_u64 v[0:1], s[22:23], 0, v[0:1]
	v_lshl_add_u64 v[100:101], v[0:1], 0, v[152:153]
	v_lshlrev_b32_e32 v0, 2, v32
	v_lshrrev_b32_e32 v1, 2, v32
	v_lshl_add_u64 v[98:99], v[2:3], 0, v[152:153]
	v_and_b32_e32 v0, 48, v0
	v_and_b32_e32 v1, 4, v1
	v_and_b32_e32 v2, 3, v32
	v_or3_b32 v33, v2, v1, v0
	global_load_dwordx4 v[0:3], v[98:99], off
	v_lshl_add_u64 v[4:5], v[98:99], 0, s[76:77]
	global_load_dwordx4 v[4:7], v[4:5], off
	v_lshl_add_u64 v[8:9], v[98:99], 0, s[8:9]
	global_load_dwordx4 v[8:11], v[8:9], off
	v_lshl_add_u64 v[12:13], v[98:99], 0, s[78:79]
	global_load_dwordx4 v[12:15], v[12:13], off
	global_load_dwordx4 v[16:19], v[100:101], off
	v_lshl_add_u64 v[20:21], v[100:101], 0, s[76:77]
	global_load_dwordx4 v[20:23], v[20:21], off
	v_lshl_add_u64 v[24:25], v[100:101], 0, s[8:9]
	global_load_dwordx4 v[24:27], v[24:25], off
	v_lshl_add_u64 v[28:29], v[100:101], 0, s[78:79]
	global_load_dwordx4 v[28:31], v[28:29], off
	v_lshl_add_u64 v[36:37], v[98:99], 0, s[80:81]
	global_load_dwordx4 v[40:43], v[36:37], off
	s_mov_b64 s[24:25], 0x10080
	v_lshl_add_u64 v[36:37], v[98:99], 0, s[24:25]
	global_load_dwordx4 v[44:47], v[36:37], off
	s_mov_b64 s[22:23], 0x20080
	v_lshl_add_u64 v[36:37], v[98:99], 0, s[22:23]
	global_load_dwordx4 v[48:51], v[36:37], off
	s_mov_b64 s[20:21], 0x30080
	v_lshl_add_u64 v[36:37], v[98:99], 0, s[20:21]
	global_load_dwordx4 v[52:55], v[36:37], off
	v_lshl_add_u64 v[34:35], v[100:101], 0, s[80:81]
	global_load_dwordx4 v[56:59], v[34:35], off
	v_lshl_add_u64 v[34:35], v[100:101], 0, s[24:25]
	global_load_dwordx4 v[60:63], v[34:35], off
	v_lshl_add_u64 v[34:35], v[100:101], 0, s[22:23]
	global_load_dwordx4 v[64:67], v[34:35], off
	v_lshl_add_u64 v[34:35], v[100:101], 0, s[20:21]
	global_load_dwordx4 v[72:75], v[34:35], off
	s_barrier
	s_waitcnt vmcnt(8)
	v_add_u32_e32 v140, 4, v32
	v_and_b32_e32 v140, 8, v140
	v_lshlrev_b32_e32 v140, 1, v140
	v_xor_b32_e32 v140, v152, v140
	v_mad_u32_u24 v102, v32, s89, v140
	v_and_b32_e32 v39, 15, v38
	ds_write_b128 v102, v[0:3]
	ds_write_b128 v102, v[4:7] offset:4608
	ds_write_b128 v102, v[8:11] offset:9216
	ds_write_b128 v102, v[12:15] offset:13824
	v_lshrrev_b32_e32 v0, 1, v38
	v_and_or_b32 v1, v0, s74, v39
	v_and_b32_e32 v0, 48, v38
	v_add_u32_e32 v141, 4, v38
	v_and_b32_e32 v141, 8, v141
	v_lshlrev_b32_e32 v141, 1, v141
	v_xor_b32_e32 v141, v0, v141
	v_mad_u32_u24 v104, v1, s89, v141
	v_and_b32_e32 v1, 0x4f, v38
	v_mul_u32_u24_e32 v1, 0x48, v1
	v_mad_u32_u24 v103, v33, s89, v152
	v_lshl_add_u32 v105, v1, 1, v0
	v_mov_b32_e32 v0, 0
	s_mov_b64 s[82:83], 0x20080
	s_mov_b64 s[84:85], 0x30080
	v_add_u32_e32 v106, 0x9000, v103
	ds_write_b128 v103, v[16:19] offset:36864
	ds_write_b128 v103, v[20:23] offset:38016
	ds_write_b128 v103, v[24:27] offset:46080
	ds_write_b128 v103, v[28:31] offset:47232
	s_mov_b32 s19, 0
	s_movk_i32 s15, 0xc0
	v_mov_b32_e32 v1, v0
	v_mov_b32_e32 v2, v0
	v_mov_b32_e32 v3, v0
	v_mov_b32_e32 v4, v0
	v_mov_b32_e32 v5, v0
	v_mov_b32_e32 v6, v0
	v_mov_b32_e32 v7, v0
	v_mov_b32_e32 v8, v0
	v_mov_b32_e32 v9, v0
	v_mov_b32_e32 v10, v0
	v_mov_b32_e32 v11, v0
	v_mov_b32_e32 v12, v0
	v_mov_b32_e32 v13, v0
	v_mov_b32_e32 v14, v0
	v_mov_b32_e32 v15, v0
	v_mov_b32_e32 v16, v0
	v_mov_b32_e32 v17, v0
	v_mov_b32_e32 v18, v0
	v_mov_b32_e32 v19, v0
	v_mov_b32_e32 v20, v0
	v_mov_b32_e32 v21, v0
	v_mov_b32_e32 v22, v0
	v_mov_b32_e32 v23, v0
	v_mov_b32_e32 v24, v0
	v_mov_b32_e32 v25, v0
	v_mov_b32_e32 v26, v0
	v_mov_b32_e32 v27, v0
	v_mov_b32_e32 v28, v0
	v_mov_b32_e32 v29, v0
	v_mov_b32_e32 v30, v0
	v_mov_b32_e32 v31, v0
	v_mov_b32_e32 v32, v0
	v_mov_b32_e32 v33, v0
	v_mov_b32_e32 v34, v0
	v_mov_b32_e32 v35, v0
	v_mov_b32_e32 v36, v0
	v_mov_b32_e32 v37, v0
	v_mov_b32_e32 v38, v0
	v_mov_b32_e32 v39, v0
	v_mov_b32_e32 v68, v0
	v_mov_b32_e32 v69, v0
	v_mov_b32_e32 v70, v0
	v_mov_b32_e32 v71, v0
	v_mov_b32_e32 v76, v0
	v_mov_b32_e32 v77, v0
	v_mov_b32_e32 v78, v0
	v_mov_b32_e32 v79, v0
	v_mov_b32_e32 v80, v0
	v_mov_b32_e32 v81, v0
	v_mov_b32_e32 v82, v0
	v_mov_b32_e32 v83, v0
	v_mov_b32_e32 v84, v0
	v_mov_b32_e32 v85, v0
	v_mov_b32_e32 v86, v0
	v_mov_b32_e32 v87, v0
	v_mov_b32_e32 v88, v0
	v_mov_b32_e32 v89, v0
	v_mov_b32_e32 v90, v0
	v_mov_b32_e32 v91, v0
	v_mov_b32_e32 v92, v0
	v_mov_b32_e32 v93, v0
	v_mov_b32_e32 v94, v0
	v_mov_b32_e32 v95, v0
	s_waitcnt lgkmcnt(0)
	s_barrier
